# P2 conv4: hand-written sliding-window path (one wave = 32 rows x 512 columns, each input row loaded once, 45 loads in flight per wave with a constant counted vmcnt)
# speedup vs baseline: 1.0002x; 1.0002x over previous
.LBB0_669:
	s_or_b64 exec, exec, s[38:39]
	s_cmp_eq_u32 s92, 0x100
	s_cbranch_scc0 .Lp2b_compiled
	v_mbcnt_lo_u32_b32 v0, -1, 0
	v_mbcnt_hi_u32_b32 v0, -1, v0
	s_lshl_b32 s4, s2, 3
	s_add_i32 s4, s4, s33
	s_lshl_b32 s4, s4, 5
	v_lshlrev_b32_e32 v1, 4, v0
	v_lshlrev_b32_e32 v2, 5, v0
	v_add_u32_e32 v3, 0x1000, v2
	s_lshl_b32 s5, s4, 10
	s_mov_b32 s6, 0
	s_add_u32 s8, s96, 0x1d800000
	s_addc_u32 s9, s97, 0
	s_add_u32 s8, s8, s5
	s_addc_u32 s9, s9, 0
	s_add_u32 s10, s96, 0x27800000
	s_addc_u32 s11, s97, 0
	s_add_u32 s10, s10, s5
	s_addc_u32 s11, s11, 0
	s_and_b32 s12, s4, 0x7ff
	s_cmp_eq_u32 s12, 0
	s_cselect_b32 s12, 0, 0xc00
	s_sub_u32 s14, s8, s12
	s_subb_u32 s15, s9, 0
	global_load_dwordx4 v[8:11], v2, s[70:71]
	global_load_dwordx4 v[12:15], v2, s[70:71] offset:16
	global_load_dwordx4 v[16:19], v2, s[70:71] offset:2048
	global_load_dwordx4 v[20:23], v2, s[70:71] offset:2064
	global_load_dwordx4 v[24:27], v3, s[70:71]
	global_load_dwordx4 v[28:31], v3, s[70:71] offset:16
	global_load_dwordx4 v[32:35], v3, s[70:71] offset:2048
	global_load_dwordx4 v[36:39], v3, s[70:71] offset:2064
	global_load_dwordx4 v[72:75], v2, s[72:73]
	global_load_dwordx4 v[76:79], v2, s[72:73] offset:16
	global_load_dwordx4 v[100:103], v1, s[14:15]
	global_load_dwordx4 v[104:107], v1, s[14:15] offset:1024
	global_load_dwordx4 v[108:111], v1, s[14:15] offset:2048
	global_load_dwordx4 v[112:115], v1, s[8:9]
	global_load_dwordx4 v[116:119], v1, s[8:9] offset:1024
	global_load_dwordx4 v[120:123], v1, s[8:9] offset:2048
	global_load_dwordx4 v[124:127], v1, s[8:9] offset:3072
	s_add_u32 s8, s8, 0x1000
	s_addc_u32 s9, s9, 0
	global_load_dwordx4 v[128:131], v1, s[8:9]
	global_load_dwordx4 v[132:135], v1, s[8:9] offset:1024
	global_load_dwordx4 v[136:139], v1, s[8:9] offset:2048
	global_load_dwordx4 v[140:143], v1, s[8:9] offset:3072
	s_add_u32 s8, s8, 0x1000
	s_addc_u32 s9, s9, 0
	global_load_dwordx4 v[144:147], v1, s[8:9]
	global_load_dwordx4 v[148:151], v1, s[8:9] offset:1024
	global_load_dwordx4 v[152:155], v1, s[8:9] offset:2048
	global_load_dwordx4 v[156:159], v1, s[8:9] offset:3072
	s_add_u32 s8, s8, 0x1000
	s_addc_u32 s9, s9, 0
	global_load_dwordx4 v[160:163], v1, s[8:9]
	global_load_dwordx4 v[164:167], v1, s[8:9] offset:1024
	global_load_dwordx4 v[168:171], v1, s[8:9] offset:2048
	global_load_dwordx4 v[172:175], v1, s[8:9] offset:3072
	s_add_u32 s8, s8, 0x1000
	s_addc_u32 s9, s9, 0
	global_load_dwordx4 v[176:179], v1, s[8:9]
	global_load_dwordx4 v[180:183], v1, s[8:9] offset:1024
	global_load_dwordx4 v[184:187], v1, s[8:9] offset:2048
	global_load_dwordx4 v[188:191], v1, s[8:9] offset:3072
	s_add_u32 s8, s8, 0x1000
	s_addc_u32 s9, s9, 0
	global_load_dwordx4 v[192:195], v1, s[8:9]
	global_load_dwordx4 v[196:199], v1, s[8:9] offset:1024
	global_load_dwordx4 v[200:203], v1, s[8:9] offset:2048
	global_load_dwordx4 v[204:207], v1, s[8:9] offset:3072
	s_add_u32 s8, s8, 0x1000
	s_addc_u32 s9, s9, 0
	global_load_dwordx4 v[208:211], v1, s[8:9]
	global_load_dwordx4 v[212:215], v1, s[8:9] offset:1024
	global_load_dwordx4 v[216:219], v1, s[8:9] offset:2048
	global_load_dwordx4 v[220:223], v1, s[8:9] offset:3072
	s_add_u32 s8, s8, 0x1000
	s_addc_u32 s9, s9, 0
	global_load_dwordx4 v[224:227], v1, s[8:9]
	global_load_dwordx4 v[228:231], v1, s[8:9] offset:1024
	global_load_dwordx4 v[232:235], v1, s[8:9] offset:2048
	global_load_dwordx4 v[236:239], v1, s[8:9] offset:3072
	s_waitcnt vmcnt(32)
	v_lshlrev_b32_e32 v48, 16, v100
	v_and_b32_e32 v49, 0xffff0000, v100
	v_lshlrev_b32_e32 v50, 16, v101
	v_and_b32_e32 v51, 0xffff0000, v101
	v_lshlrev_b32_e32 v52, 16, v102
	v_and_b32_e32 v53, 0xffff0000, v102
	v_lshlrev_b32_e32 v54, 16, v103
	v_and_b32_e32 v55, 0xffff0000, v103
	v_lshlrev_b32_e32 v56, 16, v104
	v_and_b32_e32 v57, 0xffff0000, v104
	v_lshlrev_b32_e32 v58, 16, v105
	v_and_b32_e32 v59, 0xffff0000, v105
	v_lshlrev_b32_e32 v60, 16, v106
	v_and_b32_e32 v61, 0xffff0000, v106
	v_lshlrev_b32_e32 v62, 16, v107
	v_and_b32_e32 v63, 0xffff0000, v107
	v_lshlrev_b32_e32 v64, 16, v108
	v_and_b32_e32 v65, 0xffff0000, v108
	v_lshlrev_b32_e32 v66, 16, v109
	v_and_b32_e32 v67, 0xffff0000, v109
	v_lshlrev_b32_e32 v68, 16, v110
	v_and_b32_e32 v69, 0xffff0000, v110
	v_lshlrev_b32_e32 v70, 16, v111
	v_and_b32_e32 v71, 0xffff0000, v111
	s_cmp_eq_u32 s12, 0
	s_cbranch_scc0 .Lp2b_halo
	v_mov_b64_e32 v[48:49], 0
	v_mov_b64_e32 v[50:51], 0
	v_mov_b64_e32 v[52:53], 0
	v_mov_b64_e32 v[54:55], 0
	v_mov_b64_e32 v[56:57], 0
	v_mov_b64_e32 v[58:59], 0
	v_mov_b64_e32 v[60:61], 0
	v_mov_b64_e32 v[62:63], 0
	v_mov_b64_e32 v[64:65], 0
	v_mov_b64_e32 v[66:67], 0
	v_mov_b64_e32 v[68:69], 0
	v_mov_b64_e32 v[70:71], 0
.Lp2b_halo:
	s_waitcnt vmcnt(31)
	v_lshlrev_b32_e32 v40, 16, v112
	v_and_b32_e32 v41, 0xffff0000, v112
	v_lshlrev_b32_e32 v42, 16, v113
	v_and_b32_e32 v43, 0xffff0000, v113
	v_lshlrev_b32_e32 v44, 16, v114
	v_and_b32_e32 v45, 0xffff0000, v114
	v_lshlrev_b32_e32 v46, 16, v115
	v_and_b32_e32 v47, 0xffff0000, v115
	v_pk_fma_f32 v[80:81], v[48:49], v[8:9], v[72:73]
	v_pk_fma_f32 v[82:83], v[50:51], v[10:11], v[74:75]
	v_pk_fma_f32 v[84:85], v[52:53], v[12:13], v[76:77]
	v_pk_fma_f32 v[86:87], v[54:55], v[14:15], v[78:79]
	v_pk_fma_f32 v[80:81], v[56:57], v[16:17], v[80:81]
	v_pk_fma_f32 v[82:83], v[58:59], v[18:19], v[82:83]
	v_pk_fma_f32 v[84:85], v[60:61], v[20:21], v[84:85]
	v_pk_fma_f32 v[86:87], v[62:63], v[22:23], v[86:87]
	v_pk_fma_f32 v[80:81], v[64:65], v[24:25], v[80:81]
	v_pk_fma_f32 v[82:83], v[66:67], v[26:27], v[82:83]
	v_pk_fma_f32 v[84:85], v[68:69], v[28:29], v[84:85]
	v_pk_fma_f32 v[86:87], v[70:71], v[30:31], v[86:87]
	v_pk_fma_f32 v[80:81], v[40:41], v[32:33], v[80:81]
	v_pk_fma_f32 v[82:83], v[42:43], v[34:35], v[82:83]
	v_pk_fma_f32 v[84:85], v[44:45], v[36:37], v[84:85]
	v_pk_fma_f32 v[86:87], v[46:47], v[38:39], v[86:87]
	v_cvt_pk_bf16_f32 v88, v80, v81
	v_cvt_pk_bf16_f32 v89, v82, v83
	v_cvt_pk_bf16_f32 v90, v84, v85
	v_cvt_pk_bf16_f32 v91, v86, v87
	global_store_dwordx4 v1, v[88:91], s[10:11]
	s_nop 1
	s_waitcnt vmcnt(31)
	v_lshlrev_b32_e32 v48, 16, v116
	v_and_b32_e32 v49, 0xffff0000, v116
	v_lshlrev_b32_e32 v50, 16, v117
	v_and_b32_e32 v51, 0xffff0000, v117
	v_lshlrev_b32_e32 v52, 16, v118
	v_and_b32_e32 v53, 0xffff0000, v118
	v_lshlrev_b32_e32 v54, 16, v119
	v_and_b32_e32 v55, 0xffff0000, v119
	v_pk_fma_f32 v[80:81], v[56:57], v[8:9], v[72:73]
	v_pk_fma_f32 v[82:83], v[58:59], v[10:11], v[74:75]
	v_pk_fma_f32 v[84:85], v[60:61], v[12:13], v[76:77]
	v_pk_fma_f32 v[86:87], v[62:63], v[14:15], v[78:79]
	v_pk_fma_f32 v[80:81], v[64:65], v[16:17], v[80:81]
	v_pk_fma_f32 v[82:83], v[66:67], v[18:19], v[82:83]
	v_pk_fma_f32 v[84:85], v[68:69], v[20:21], v[84:85]
	v_pk_fma_f32 v[86:87], v[70:71], v[22:23], v[86:87]
	v_pk_fma_f32 v[80:81], v[40:41], v[24:25], v[80:81]
	v_pk_fma_f32 v[82:83], v[42:43], v[26:27], v[82:83]
	v_pk_fma_f32 v[84:85], v[44:45], v[28:29], v[84:85]
	v_pk_fma_f32 v[86:87], v[46:47], v[30:31], v[86:87]
	v_pk_fma_f32 v[80:81], v[48:49], v[32:33], v[80:81]
	v_pk_fma_f32 v[82:83], v[50:51], v[34:35], v[82:83]
	v_pk_fma_f32 v[84:85], v[52:53], v[36:37], v[84:85]
	v_pk_fma_f32 v[86:87], v[54:55], v[38:39], v[86:87]
	v_cvt_pk_bf16_f32 v88, v80, v81
	v_cvt_pk_bf16_f32 v89, v82, v83
	v_cvt_pk_bf16_f32 v90, v84, v85
	v_cvt_pk_bf16_f32 v91, v86, v87
	global_store_dwordx4 v1, v[88:91], s[10:11] offset:1024
	s_nop 1
	s_waitcnt vmcnt(31)
	v_lshlrev_b32_e32 v56, 16, v120
	v_and_b32_e32 v57, 0xffff0000, v120
	v_lshlrev_b32_e32 v58, 16, v121
	v_and_b32_e32 v59, 0xffff0000, v121
	v_lshlrev_b32_e32 v60, 16, v122
	v_and_b32_e32 v61, 0xffff0000, v122
	v_lshlrev_b32_e32 v62, 16, v123
	v_and_b32_e32 v63, 0xffff0000, v123
	v_pk_fma_f32 v[80:81], v[64:65], v[8:9], v[72:73]
	v_pk_fma_f32 v[82:83], v[66:67], v[10:11], v[74:75]
	v_pk_fma_f32 v[84:85], v[68:69], v[12:13], v[76:77]
	v_pk_fma_f32 v[86:87], v[70:71], v[14:15], v[78:79]
	v_pk_fma_f32 v[80:81], v[40:41], v[16:17], v[80:81]
	v_pk_fma_f32 v[82:83], v[42:43], v[18:19], v[82:83]
	v_pk_fma_f32 v[84:85], v[44:45], v[20:21], v[84:85]
	v_pk_fma_f32 v[86:87], v[46:47], v[22:23], v[86:87]
	v_pk_fma_f32 v[80:81], v[48:49], v[24:25], v[80:81]
	v_pk_fma_f32 v[82:83], v[50:51], v[26:27], v[82:83]
	v_pk_fma_f32 v[84:85], v[52:53], v[28:29], v[84:85]
	v_pk_fma_f32 v[86:87], v[54:55], v[30:31], v[86:87]
	v_pk_fma_f32 v[80:81], v[56:57], v[32:33], v[80:81]
	v_pk_fma_f32 v[82:83], v[58:59], v[34:35], v[82:83]
	v_pk_fma_f32 v[84:85], v[60:61], v[36:37], v[84:85]
	v_pk_fma_f32 v[86:87], v[62:63], v[38:39], v[86:87]
	v_cvt_pk_bf16_f32 v88, v80, v81
	v_cvt_pk_bf16_f32 v89, v82, v83
	v_cvt_pk_bf16_f32 v90, v84, v85
	v_cvt_pk_bf16_f32 v91, v86, v87
	global_store_dwordx4 v1, v[88:91], s[10:11] offset:2048
	s_nop 1
	s_waitcnt vmcnt(31)
	v_lshlrev_b32_e32 v64, 16, v124
	v_and_b32_e32 v65, 0xffff0000, v124
	v_lshlrev_b32_e32 v66, 16, v125
	v_and_b32_e32 v67, 0xffff0000, v125
	v_lshlrev_b32_e32 v68, 16, v126
	v_and_b32_e32 v69, 0xffff0000, v126
	v_lshlrev_b32_e32 v70, 16, v127
	v_and_b32_e32 v71, 0xffff0000, v127
	v_pk_fma_f32 v[80:81], v[40:41], v[8:9], v[72:73]
	v_pk_fma_f32 v[82:83], v[42:43], v[10:11], v[74:75]
	v_pk_fma_f32 v[84:85], v[44:45], v[12:13], v[76:77]
	v_pk_fma_f32 v[86:87], v[46:47], v[14:15], v[78:79]
	v_pk_fma_f32 v[80:81], v[48:49], v[16:17], v[80:81]
	v_pk_fma_f32 v[82:83], v[50:51], v[18:19], v[82:83]
	v_pk_fma_f32 v[84:85], v[52:53], v[20:21], v[84:85]
	v_pk_fma_f32 v[86:87], v[54:55], v[22:23], v[86:87]
	v_pk_fma_f32 v[80:81], v[56:57], v[24:25], v[80:81]
	v_pk_fma_f32 v[82:83], v[58:59], v[26:27], v[82:83]
	v_pk_fma_f32 v[84:85], v[60:61], v[28:29], v[84:85]
	v_pk_fma_f32 v[86:87], v[62:63], v[30:31], v[86:87]
	v_pk_fma_f32 v[80:81], v[64:65], v[32:33], v[80:81]
	v_pk_fma_f32 v[82:83], v[66:67], v[34:35], v[82:83]
	v_pk_fma_f32 v[84:85], v[68:69], v[36:37], v[84:85]
	v_pk_fma_f32 v[86:87], v[70:71], v[38:39], v[86:87]
	v_cvt_pk_bf16_f32 v88, v80, v81
	v_cvt_pk_bf16_f32 v89, v82, v83
	v_cvt_pk_bf16_f32 v90, v84, v85
	v_cvt_pk_bf16_f32 v91, v86, v87
	global_store_dwordx4 v1, v[88:91], s[10:11] offset:3072
	s_nop 1
	s_waitcnt vmcnt(31)
	v_lshlrev_b32_e32 v40, 16, v128
	v_and_b32_e32 v41, 0xffff0000, v128
	v_lshlrev_b32_e32 v42, 16, v129
	v_and_b32_e32 v43, 0xffff0000, v129
	v_lshlrev_b32_e32 v44, 16, v130
	v_and_b32_e32 v45, 0xffff0000, v130
	v_lshlrev_b32_e32 v46, 16, v131
	v_and_b32_e32 v47, 0xffff0000, v131
	v_pk_fma_f32 v[80:81], v[48:49], v[8:9], v[72:73]
	v_pk_fma_f32 v[82:83], v[50:51], v[10:11], v[74:75]
	v_pk_fma_f32 v[84:85], v[52:53], v[12:13], v[76:77]
	v_pk_fma_f32 v[86:87], v[54:55], v[14:15], v[78:79]
	v_pk_fma_f32 v[80:81], v[56:57], v[16:17], v[80:81]
	v_pk_fma_f32 v[82:83], v[58:59], v[18:19], v[82:83]
	v_pk_fma_f32 v[84:85], v[60:61], v[20:21], v[84:85]
	v_pk_fma_f32 v[86:87], v[62:63], v[22:23], v[86:87]
	v_pk_fma_f32 v[80:81], v[64:65], v[24:25], v[80:81]
	v_pk_fma_f32 v[82:83], v[66:67], v[26:27], v[82:83]
	v_pk_fma_f32 v[84:85], v[68:69], v[28:29], v[84:85]
	v_pk_fma_f32 v[86:87], v[70:71], v[30:31], v[86:87]
	v_pk_fma_f32 v[80:81], v[40:41], v[32:33], v[80:81]
	v_pk_fma_f32 v[82:83], v[42:43], v[34:35], v[82:83]
	v_pk_fma_f32 v[84:85], v[44:45], v[36:37], v[84:85]
	v_pk_fma_f32 v[86:87], v[46:47], v[38:39], v[86:87]
	v_cvt_pk_bf16_f32 v88, v80, v81
	v_cvt_pk_bf16_f32 v89, v82, v83
	v_cvt_pk_bf16_f32 v90, v84, v85
	v_cvt_pk_bf16_f32 v91, v86, v87
	s_add_u32 s10, s10, 0x1000
	s_addc_u32 s11, s11, 0
	global_store_dwordx4 v1, v[88:91], s[10:11]
	s_nop 1
	s_waitcnt vmcnt(31)
	v_lshlrev_b32_e32 v48, 16, v132
	v_and_b32_e32 v49, 0xffff0000, v132
	v_lshlrev_b32_e32 v50, 16, v133
	v_and_b32_e32 v51, 0xffff0000, v133
	v_lshlrev_b32_e32 v52, 16, v134
	v_and_b32_e32 v53, 0xffff0000, v134
	v_lshlrev_b32_e32 v54, 16, v135
	v_and_b32_e32 v55, 0xffff0000, v135
	v_pk_fma_f32 v[80:81], v[56:57], v[8:9], v[72:73]
	v_pk_fma_f32 v[82:83], v[58:59], v[10:11], v[74:75]
	v_pk_fma_f32 v[84:85], v[60:61], v[12:13], v[76:77]
	v_pk_fma_f32 v[86:87], v[62:63], v[14:15], v[78:79]
	v_pk_fma_f32 v[80:81], v[64:65], v[16:17], v[80:81]
	v_pk_fma_f32 v[82:83], v[66:67], v[18:19], v[82:83]
	v_pk_fma_f32 v[84:85], v[68:69], v[20:21], v[84:85]
	v_pk_fma_f32 v[86:87], v[70:71], v[22:23], v[86:87]
	v_pk_fma_f32 v[80:81], v[40:41], v[24:25], v[80:81]
	v_pk_fma_f32 v[82:83], v[42:43], v[26:27], v[82:83]
	v_pk_fma_f32 v[84:85], v[44:45], v[28:29], v[84:85]
	v_pk_fma_f32 v[86:87], v[46:47], v[30:31], v[86:87]
	v_pk_fma_f32 v[80:81], v[48:49], v[32:33], v[80:81]
	v_pk_fma_f32 v[82:83], v[50:51], v[34:35], v[82:83]
	v_pk_fma_f32 v[84:85], v[52:53], v[36:37], v[84:85]
	v_pk_fma_f32 v[86:87], v[54:55], v[38:39], v[86:87]
	v_cvt_pk_bf16_f32 v88, v80, v81
	v_cvt_pk_bf16_f32 v89, v82, v83
	v_cvt_pk_bf16_f32 v90, v84, v85
	v_cvt_pk_bf16_f32 v91, v86, v87
	global_store_dwordx4 v1, v[88:91], s[10:11] offset:1024
	s_nop 1
	s_waitcnt vmcnt(31)
	v_lshlrev_b32_e32 v56, 16, v136
	v_and_b32_e32 v57, 0xffff0000, v136
	v_lshlrev_b32_e32 v58, 16, v137
	v_and_b32_e32 v59, 0xffff0000, v137
	v_lshlrev_b32_e32 v60, 16, v138
	v_and_b32_e32 v61, 0xffff0000, v138
	v_lshlrev_b32_e32 v62, 16, v139
	v_and_b32_e32 v63, 0xffff0000, v139
	v_pk_fma_f32 v[80:81], v[64:65], v[8:9], v[72:73]
	v_pk_fma_f32 v[82:83], v[66:67], v[10:11], v[74:75]
	v_pk_fma_f32 v[84:85], v[68:69], v[12:13], v[76:77]
	v_pk_fma_f32 v[86:87], v[70:71], v[14:15], v[78:79]
	v_pk_fma_f32 v[80:81], v[40:41], v[16:17], v[80:81]
	v_pk_fma_f32 v[82:83], v[42:43], v[18:19], v[82:83]
	v_pk_fma_f32 v[84:85], v[44:45], v[20:21], v[84:85]
	v_pk_fma_f32 v[86:87], v[46:47], v[22:23], v[86:87]
	v_pk_fma_f32 v[80:81], v[48:49], v[24:25], v[80:81]
	v_pk_fma_f32 v[82:83], v[50:51], v[26:27], v[82:83]
	v_pk_fma_f32 v[84:85], v[52:53], v[28:29], v[84:85]
	v_pk_fma_f32 v[86:87], v[54:55], v[30:31], v[86:87]
	v_pk_fma_f32 v[80:81], v[56:57], v[32:33], v[80:81]
	v_pk_fma_f32 v[82:83], v[58:59], v[34:35], v[82:83]
	v_pk_fma_f32 v[84:85], v[60:61], v[36:37], v[84:85]
	v_pk_fma_f32 v[86:87], v[62:63], v[38:39], v[86:87]
	v_cvt_pk_bf16_f32 v88, v80, v81
	v_cvt_pk_bf16_f32 v89, v82, v83
	v_cvt_pk_bf16_f32 v90, v84, v85
	v_cvt_pk_bf16_f32 v91, v86, v87
	global_store_dwordx4 v1, v[88:91], s[10:11] offset:2048
	s_nop 1
	s_waitcnt vmcnt(31)
	v_lshlrev_b32_e32 v64, 16, v140
	v_and_b32_e32 v65, 0xffff0000, v140
	v_lshlrev_b32_e32 v66, 16, v141
	v_and_b32_e32 v67, 0xffff0000, v141
	v_lshlrev_b32_e32 v68, 16, v142
	v_and_b32_e32 v69, 0xffff0000, v142
	v_lshlrev_b32_e32 v70, 16, v143
	v_and_b32_e32 v71, 0xffff0000, v143
	v_pk_fma_f32 v[80:81], v[40:41], v[8:9], v[72:73]
	v_pk_fma_f32 v[82:83], v[42:43], v[10:11], v[74:75]
	v_pk_fma_f32 v[84:85], v[44:45], v[12:13], v[76:77]
	v_pk_fma_f32 v[86:87], v[46:47], v[14:15], v[78:79]
	v_pk_fma_f32 v[80:81], v[48:49], v[16:17], v[80:81]
	v_pk_fma_f32 v[82:83], v[50:51], v[18:19], v[82:83]
	v_pk_fma_f32 v[84:85], v[52:53], v[20:21], v[84:85]
	v_pk_fma_f32 v[86:87], v[54:55], v[22:23], v[86:87]
	v_pk_fma_f32 v[80:81], v[56:57], v[24:25], v[80:81]
	v_pk_fma_f32 v[82:83], v[58:59], v[26:27], v[82:83]
	v_pk_fma_f32 v[84:85], v[60:61], v[28:29], v[84:85]
	v_pk_fma_f32 v[86:87], v[62:63], v[30:31], v[86:87]
	v_pk_fma_f32 v[80:81], v[64:65], v[32:33], v[80:81]
	v_pk_fma_f32 v[82:83], v[66:67], v[34:35], v[82:83]
	v_pk_fma_f32 v[84:85], v[68:69], v[36:37], v[84:85]
	v_pk_fma_f32 v[86:87], v[70:71], v[38:39], v[86:87]
	v_cvt_pk_bf16_f32 v88, v80, v81
	v_cvt_pk_bf16_f32 v89, v82, v83
	v_cvt_pk_bf16_f32 v90, v84, v85
	v_cvt_pk_bf16_f32 v91, v86, v87
	global_store_dwordx4 v1, v[88:91], s[10:11] offset:3072
	s_nop 1
	s_waitcnt vmcnt(31)
	v_lshlrev_b32_e32 v40, 16, v144
	v_and_b32_e32 v41, 0xffff0000, v144
	v_lshlrev_b32_e32 v42, 16, v145
	v_and_b32_e32 v43, 0xffff0000, v145
	v_lshlrev_b32_e32 v44, 16, v146
	v_and_b32_e32 v45, 0xffff0000, v146
	v_lshlrev_b32_e32 v46, 16, v147
	v_and_b32_e32 v47, 0xffff0000, v147
	v_pk_fma_f32 v[80:81], v[48:49], v[8:9], v[72:73]
	v_pk_fma_f32 v[82:83], v[50:51], v[10:11], v[74:75]
	v_pk_fma_f32 v[84:85], v[52:53], v[12:13], v[76:77]
	v_pk_fma_f32 v[86:87], v[54:55], v[14:15], v[78:79]
	v_pk_fma_f32 v[80:81], v[56:57], v[16:17], v[80:81]
	v_pk_fma_f32 v[82:83], v[58:59], v[18:19], v[82:83]
	v_pk_fma_f32 v[84:85], v[60:61], v[20:21], v[84:85]
	v_pk_fma_f32 v[86:87], v[62:63], v[22:23], v[86:87]
	v_pk_fma_f32 v[80:81], v[64:65], v[24:25], v[80:81]
	v_pk_fma_f32 v[82:83], v[66:67], v[26:27], v[82:83]
	v_pk_fma_f32 v[84:85], v[68:69], v[28:29], v[84:85]
	v_pk_fma_f32 v[86:87], v[70:71], v[30:31], v[86:87]
	v_pk_fma_f32 v[80:81], v[40:41], v[32:33], v[80:81]
	v_pk_fma_f32 v[82:83], v[42:43], v[34:35], v[82:83]
	v_pk_fma_f32 v[84:85], v[44:45], v[36:37], v[84:85]
	v_pk_fma_f32 v[86:87], v[46:47], v[38:39], v[86:87]
	v_cvt_pk_bf16_f32 v88, v80, v81
	v_cvt_pk_bf16_f32 v89, v82, v83
	v_cvt_pk_bf16_f32 v90, v84, v85
	v_cvt_pk_bf16_f32 v91, v86, v87
	s_add_u32 s10, s10, 0x1000
	s_addc_u32 s11, s11, 0
	global_store_dwordx4 v1, v[88:91], s[10:11]
	s_nop 1
	s_waitcnt vmcnt(31)
	v_lshlrev_b32_e32 v48, 16, v148
	v_and_b32_e32 v49, 0xffff0000, v148
	v_lshlrev_b32_e32 v50, 16, v149
	v_and_b32_e32 v51, 0xffff0000, v149
	v_lshlrev_b32_e32 v52, 16, v150
	v_and_b32_e32 v53, 0xffff0000, v150
	v_lshlrev_b32_e32 v54, 16, v151
	v_and_b32_e32 v55, 0xffff0000, v151
	v_pk_fma_f32 v[80:81], v[56:57], v[8:9], v[72:73]
	v_pk_fma_f32 v[82:83], v[58:59], v[10:11], v[74:75]
	v_pk_fma_f32 v[84:85], v[60:61], v[12:13], v[76:77]
	v_pk_fma_f32 v[86:87], v[62:63], v[14:15], v[78:79]
	v_pk_fma_f32 v[80:81], v[64:65], v[16:17], v[80:81]
	v_pk_fma_f32 v[82:83], v[66:67], v[18:19], v[82:83]
	v_pk_fma_f32 v[84:85], v[68:69], v[20:21], v[84:85]
	v_pk_fma_f32 v[86:87], v[70:71], v[22:23], v[86:87]
	v_pk_fma_f32 v[80:81], v[40:41], v[24:25], v[80:81]
	v_pk_fma_f32 v[82:83], v[42:43], v[26:27], v[82:83]
	v_pk_fma_f32 v[84:85], v[44:45], v[28:29], v[84:85]
	v_pk_fma_f32 v[86:87], v[46:47], v[30:31], v[86:87]
	v_pk_fma_f32 v[80:81], v[48:49], v[32:33], v[80:81]
	v_pk_fma_f32 v[82:83], v[50:51], v[34:35], v[82:83]
	v_pk_fma_f32 v[84:85], v[52:53], v[36:37], v[84:85]
	v_pk_fma_f32 v[86:87], v[54:55], v[38:39], v[86:87]
	v_cvt_pk_bf16_f32 v88, v80, v81
	v_cvt_pk_bf16_f32 v89, v82, v83
	v_cvt_pk_bf16_f32 v90, v84, v85
	v_cvt_pk_bf16_f32 v91, v86, v87
	global_store_dwordx4 v1, v[88:91], s[10:11] offset:1024
	s_nop 1
	s_waitcnt vmcnt(31)
	v_lshlrev_b32_e32 v56, 16, v152
	v_and_b32_e32 v57, 0xffff0000, v152
	v_lshlrev_b32_e32 v58, 16, v153
	v_and_b32_e32 v59, 0xffff0000, v153
	v_lshlrev_b32_e32 v60, 16, v154
	v_and_b32_e32 v61, 0xffff0000, v154
	v_lshlrev_b32_e32 v62, 16, v155
	v_and_b32_e32 v63, 0xffff0000, v155
	v_pk_fma_f32 v[80:81], v[64:65], v[8:9], v[72:73]
	v_pk_fma_f32 v[82:83], v[66:67], v[10:11], v[74:75]
	v_pk_fma_f32 v[84:85], v[68:69], v[12:13], v[76:77]
	v_pk_fma_f32 v[86:87], v[70:71], v[14:15], v[78:79]
	v_pk_fma_f32 v[80:81], v[40:41], v[16:17], v[80:81]
	v_pk_fma_f32 v[82:83], v[42:43], v[18:19], v[82:83]
	v_pk_fma_f32 v[84:85], v[44:45], v[20:21], v[84:85]
	v_pk_fma_f32 v[86:87], v[46:47], v[22:23], v[86:87]
	v_pk_fma_f32 v[80:81], v[48:49], v[24:25], v[80:81]
	v_pk_fma_f32 v[82:83], v[50:51], v[26:27], v[82:83]
	v_pk_fma_f32 v[84:85], v[52:53], v[28:29], v[84:85]
	v_pk_fma_f32 v[86:87], v[54:55], v[30:31], v[86:87]
	v_pk_fma_f32 v[80:81], v[56:57], v[32:33], v[80:81]
	v_pk_fma_f32 v[82:83], v[58:59], v[34:35], v[82:83]
	v_pk_fma_f32 v[84:85], v[60:61], v[36:37], v[84:85]
	v_pk_fma_f32 v[86:87], v[62:63], v[38:39], v[86:87]
	v_cvt_pk_bf16_f32 v88, v80, v81
	v_cvt_pk_bf16_f32 v89, v82, v83
	v_cvt_pk_bf16_f32 v90, v84, v85
	v_cvt_pk_bf16_f32 v91, v86, v87
	global_store_dwordx4 v1, v[88:91], s[10:11] offset:2048
	s_nop 1
	s_waitcnt vmcnt(31)
	v_lshlrev_b32_e32 v64, 16, v156
	v_and_b32_e32 v65, 0xffff0000, v156
	v_lshlrev_b32_e32 v66, 16, v157
	v_and_b32_e32 v67, 0xffff0000, v157
	v_lshlrev_b32_e32 v68, 16, v158
	v_and_b32_e32 v69, 0xffff0000, v158
	v_lshlrev_b32_e32 v70, 16, v159
	v_and_b32_e32 v71, 0xffff0000, v159
	v_pk_fma_f32 v[80:81], v[40:41], v[8:9], v[72:73]
	v_pk_fma_f32 v[82:83], v[42:43], v[10:11], v[74:75]
	v_pk_fma_f32 v[84:85], v[44:45], v[12:13], v[76:77]
	v_pk_fma_f32 v[86:87], v[46:47], v[14:15], v[78:79]
	v_pk_fma_f32 v[80:81], v[48:49], v[16:17], v[80:81]
	v_pk_fma_f32 v[82:83], v[50:51], v[18:19], v[82:83]
	v_pk_fma_f32 v[84:85], v[52:53], v[20:21], v[84:85]
	v_pk_fma_f32 v[86:87], v[54:55], v[22:23], v[86:87]
	v_pk_fma_f32 v[80:81], v[56:57], v[24:25], v[80:81]
	v_pk_fma_f32 v[82:83], v[58:59], v[26:27], v[82:83]
	v_pk_fma_f32 v[84:85], v[60:61], v[28:29], v[84:85]
	v_pk_fma_f32 v[86:87], v[62:63], v[30:31], v[86:87]
	v_pk_fma_f32 v[80:81], v[64:65], v[32:33], v[80:81]
	v_pk_fma_f32 v[82:83], v[66:67], v[34:35], v[82:83]
	v_pk_fma_f32 v[84:85], v[68:69], v[36:37], v[84:85]
	v_pk_fma_f32 v[86:87], v[70:71], v[38:39], v[86:87]
	v_cvt_pk_bf16_f32 v88, v80, v81
	v_cvt_pk_bf16_f32 v89, v82, v83
	v_cvt_pk_bf16_f32 v90, v84, v85
	v_cvt_pk_bf16_f32 v91, v86, v87
	global_store_dwordx4 v1, v[88:91], s[10:11] offset:3072
	s_nop 1
	s_waitcnt vmcnt(31)
	v_lshlrev_b32_e32 v40, 16, v160
	v_and_b32_e32 v41, 0xffff0000, v160
	v_lshlrev_b32_e32 v42, 16, v161
	v_and_b32_e32 v43, 0xffff0000, v161
	v_lshlrev_b32_e32 v44, 16, v162
	v_and_b32_e32 v45, 0xffff0000, v162
	v_lshlrev_b32_e32 v46, 16, v163
	v_and_b32_e32 v47, 0xffff0000, v163
	v_pk_fma_f32 v[80:81], v[48:49], v[8:9], v[72:73]
	v_pk_fma_f32 v[82:83], v[50:51], v[10:11], v[74:75]
	v_pk_fma_f32 v[84:85], v[52:53], v[12:13], v[76:77]
	v_pk_fma_f32 v[86:87], v[54:55], v[14:15], v[78:79]
	v_pk_fma_f32 v[80:81], v[56:57], v[16:17], v[80:81]
	v_pk_fma_f32 v[82:83], v[58:59], v[18:19], v[82:83]
	v_pk_fma_f32 v[84:85], v[60:61], v[20:21], v[84:85]
	v_pk_fma_f32 v[86:87], v[62:63], v[22:23], v[86:87]
	v_pk_fma_f32 v[80:81], v[64:65], v[24:25], v[80:81]
	v_pk_fma_f32 v[82:83], v[66:67], v[26:27], v[82:83]
	v_pk_fma_f32 v[84:85], v[68:69], v[28:29], v[84:85]
	v_pk_fma_f32 v[86:87], v[70:71], v[30:31], v[86:87]
	v_pk_fma_f32 v[80:81], v[40:41], v[32:33], v[80:81]
	v_pk_fma_f32 v[82:83], v[42:43], v[34:35], v[82:83]
	v_pk_fma_f32 v[84:85], v[44:45], v[36:37], v[84:85]
	v_pk_fma_f32 v[86:87], v[46:47], v[38:39], v[86:87]
	v_cvt_pk_bf16_f32 v88, v80, v81
	v_cvt_pk_bf16_f32 v89, v82, v83
	v_cvt_pk_bf16_f32 v90, v84, v85
	v_cvt_pk_bf16_f32 v91, v86, v87
	s_add_u32 s10, s10, 0x1000
	s_addc_u32 s11, s11, 0
	global_store_dwordx4 v1, v[88:91], s[10:11]
	s_nop 1
	s_waitcnt vmcnt(31)
	v_lshlrev_b32_e32 v48, 16, v164
	v_and_b32_e32 v49, 0xffff0000, v164
	v_lshlrev_b32_e32 v50, 16, v165
	v_and_b32_e32 v51, 0xffff0000, v165
	v_lshlrev_b32_e32 v52, 16, v166
	v_and_b32_e32 v53, 0xffff0000, v166
	v_lshlrev_b32_e32 v54, 16, v167
	v_and_b32_e32 v55, 0xffff0000, v167
	v_pk_fma_f32 v[80:81], v[56:57], v[8:9], v[72:73]
	v_pk_fma_f32 v[82:83], v[58:59], v[10:11], v[74:75]
	v_pk_fma_f32 v[84:85], v[60:61], v[12:13], v[76:77]
	v_pk_fma_f32 v[86:87], v[62:63], v[14:15], v[78:79]
	v_pk_fma_f32 v[80:81], v[64:65], v[16:17], v[80:81]
	v_pk_fma_f32 v[82:83], v[66:67], v[18:19], v[82:83]
	v_pk_fma_f32 v[84:85], v[68:69], v[20:21], v[84:85]
	v_pk_fma_f32 v[86:87], v[70:71], v[22:23], v[86:87]
	v_pk_fma_f32 v[80:81], v[40:41], v[24:25], v[80:81]
	v_pk_fma_f32 v[82:83], v[42:43], v[26:27], v[82:83]
	v_pk_fma_f32 v[84:85], v[44:45], v[28:29], v[84:85]
	v_pk_fma_f32 v[86:87], v[46:47], v[30:31], v[86:87]
	v_pk_fma_f32 v[80:81], v[48:49], v[32:33], v[80:81]
	v_pk_fma_f32 v[82:83], v[50:51], v[34:35], v[82:83]
	v_pk_fma_f32 v[84:85], v[52:53], v[36:37], v[84:85]
	v_pk_fma_f32 v[86:87], v[54:55], v[38:39], v[86:87]
	v_cvt_pk_bf16_f32 v88, v80, v81
	v_cvt_pk_bf16_f32 v89, v82, v83
	v_cvt_pk_bf16_f32 v90, v84, v85
	v_cvt_pk_bf16_f32 v91, v86, v87
	global_store_dwordx4 v1, v[88:91], s[10:11] offset:1024
	s_nop 1
	s_waitcnt vmcnt(31)
	v_lshlrev_b32_e32 v56, 16, v168
	v_and_b32_e32 v57, 0xffff0000, v168
	v_lshlrev_b32_e32 v58, 16, v169
	v_and_b32_e32 v59, 0xffff0000, v169
	v_lshlrev_b32_e32 v60, 16, v170
	v_and_b32_e32 v61, 0xffff0000, v170
	v_lshlrev_b32_e32 v62, 16, v171
	v_and_b32_e32 v63, 0xffff0000, v171
	v_pk_fma_f32 v[80:81], v[64:65], v[8:9], v[72:73]
	v_pk_fma_f32 v[82:83], v[66:67], v[10:11], v[74:75]
	v_pk_fma_f32 v[84:85], v[68:69], v[12:13], v[76:77]
	v_pk_fma_f32 v[86:87], v[70:71], v[14:15], v[78:79]
	v_pk_fma_f32 v[80:81], v[40:41], v[16:17], v[80:81]
	v_pk_fma_f32 v[82:83], v[42:43], v[18:19], v[82:83]
	v_pk_fma_f32 v[84:85], v[44:45], v[20:21], v[84:85]
	v_pk_fma_f32 v[86:87], v[46:47], v[22:23], v[86:87]
	v_pk_fma_f32 v[80:81], v[48:49], v[24:25], v[80:81]
	v_pk_fma_f32 v[82:83], v[50:51], v[26:27], v[82:83]
	v_pk_fma_f32 v[84:85], v[52:53], v[28:29], v[84:85]
	v_pk_fma_f32 v[86:87], v[54:55], v[30:31], v[86:87]
	v_pk_fma_f32 v[80:81], v[56:57], v[32:33], v[80:81]
	v_pk_fma_f32 v[82:83], v[58:59], v[34:35], v[82:83]
	v_pk_fma_f32 v[84:85], v[60:61], v[36:37], v[84:85]
	v_pk_fma_f32 v[86:87], v[62:63], v[38:39], v[86:87]
	v_cvt_pk_bf16_f32 v88, v80, v81
	v_cvt_pk_bf16_f32 v89, v82, v83
	v_cvt_pk_bf16_f32 v90, v84, v85
	v_cvt_pk_bf16_f32 v91, v86, v87
	global_store_dwordx4 v1, v[88:91], s[10:11] offset:2048
	s_nop 1
	s_waitcnt vmcnt(31)
	v_lshlrev_b32_e32 v64, 16, v172
	v_and_b32_e32 v65, 0xffff0000, v172
	v_lshlrev_b32_e32 v66, 16, v173
	v_and_b32_e32 v67, 0xffff0000, v173
	v_lshlrev_b32_e32 v68, 16, v174
	v_and_b32_e32 v69, 0xffff0000, v174
	v_lshlrev_b32_e32 v70, 16, v175
	v_and_b32_e32 v71, 0xffff0000, v175
	v_pk_fma_f32 v[80:81], v[40:41], v[8:9], v[72:73]
	v_pk_fma_f32 v[82:83], v[42:43], v[10:11], v[74:75]
	v_pk_fma_f32 v[84:85], v[44:45], v[12:13], v[76:77]
	v_pk_fma_f32 v[86:87], v[46:47], v[14:15], v[78:79]
	v_pk_fma_f32 v[80:81], v[48:49], v[16:17], v[80:81]
	v_pk_fma_f32 v[82:83], v[50:51], v[18:19], v[82:83]
	v_pk_fma_f32 v[84:85], v[52:53], v[20:21], v[84:85]
	v_pk_fma_f32 v[86:87], v[54:55], v[22:23], v[86:87]
	v_pk_fma_f32 v[80:81], v[56:57], v[24:25], v[80:81]
	v_pk_fma_f32 v[82:83], v[58:59], v[26:27], v[82:83]
	v_pk_fma_f32 v[84:85], v[60:61], v[28:29], v[84:85]
	v_pk_fma_f32 v[86:87], v[62:63], v[30:31], v[86:87]
	v_pk_fma_f32 v[80:81], v[64:65], v[32:33], v[80:81]
	v_pk_fma_f32 v[82:83], v[66:67], v[34:35], v[82:83]
	v_pk_fma_f32 v[84:85], v[68:69], v[36:37], v[84:85]
	v_pk_fma_f32 v[86:87], v[70:71], v[38:39], v[86:87]
	v_cvt_pk_bf16_f32 v88, v80, v81
	v_cvt_pk_bf16_f32 v89, v82, v83
	v_cvt_pk_bf16_f32 v90, v84, v85
	v_cvt_pk_bf16_f32 v91, v86, v87
	global_store_dwordx4 v1, v[88:91], s[10:11] offset:3072
	s_nop 1
	s_waitcnt vmcnt(31)
	v_lshlrev_b32_e32 v40, 16, v176
	v_and_b32_e32 v41, 0xffff0000, v176
	v_lshlrev_b32_e32 v42, 16, v177
	v_and_b32_e32 v43, 0xffff0000, v177
	v_lshlrev_b32_e32 v44, 16, v178
	v_and_b32_e32 v45, 0xffff0000, v178
	v_lshlrev_b32_e32 v46, 16, v179
	v_and_b32_e32 v47, 0xffff0000, v179
	v_pk_fma_f32 v[80:81], v[48:49], v[8:9], v[72:73]
	v_pk_fma_f32 v[82:83], v[50:51], v[10:11], v[74:75]
	v_pk_fma_f32 v[84:85], v[52:53], v[12:13], v[76:77]
	v_pk_fma_f32 v[86:87], v[54:55], v[14:15], v[78:79]
	v_pk_fma_f32 v[80:81], v[56:57], v[16:17], v[80:81]
	v_pk_fma_f32 v[82:83], v[58:59], v[18:19], v[82:83]
	v_pk_fma_f32 v[84:85], v[60:61], v[20:21], v[84:85]
	v_pk_fma_f32 v[86:87], v[62:63], v[22:23], v[86:87]
	v_pk_fma_f32 v[80:81], v[64:65], v[24:25], v[80:81]
	v_pk_fma_f32 v[82:83], v[66:67], v[26:27], v[82:83]
	v_pk_fma_f32 v[84:85], v[68:69], v[28:29], v[84:85]
	v_pk_fma_f32 v[86:87], v[70:71], v[30:31], v[86:87]
	v_pk_fma_f32 v[80:81], v[40:41], v[32:33], v[80:81]
	v_pk_fma_f32 v[82:83], v[42:43], v[34:35], v[82:83]
	v_pk_fma_f32 v[84:85], v[44:45], v[36:37], v[84:85]
	v_pk_fma_f32 v[86:87], v[46:47], v[38:39], v[86:87]
	v_cvt_pk_bf16_f32 v88, v80, v81
	v_cvt_pk_bf16_f32 v89, v82, v83
	v_cvt_pk_bf16_f32 v90, v84, v85
	v_cvt_pk_bf16_f32 v91, v86, v87
	s_add_u32 s10, s10, 0x1000
	s_addc_u32 s11, s11, 0
	global_store_dwordx4 v1, v[88:91], s[10:11]
	s_nop 1
	s_waitcnt vmcnt(31)
	v_lshlrev_b32_e32 v48, 16, v180
	v_and_b32_e32 v49, 0xffff0000, v180
	v_lshlrev_b32_e32 v50, 16, v181
	v_and_b32_e32 v51, 0xffff0000, v181
	v_lshlrev_b32_e32 v52, 16, v182
	v_and_b32_e32 v53, 0xffff0000, v182
	v_lshlrev_b32_e32 v54, 16, v183
	v_and_b32_e32 v55, 0xffff0000, v183
	v_pk_fma_f32 v[80:81], v[56:57], v[8:9], v[72:73]
	v_pk_fma_f32 v[82:83], v[58:59], v[10:11], v[74:75]
	v_pk_fma_f32 v[84:85], v[60:61], v[12:13], v[76:77]
	v_pk_fma_f32 v[86:87], v[62:63], v[14:15], v[78:79]
	v_pk_fma_f32 v[80:81], v[64:65], v[16:17], v[80:81]
	v_pk_fma_f32 v[82:83], v[66:67], v[18:19], v[82:83]
	v_pk_fma_f32 v[84:85], v[68:69], v[20:21], v[84:85]
	v_pk_fma_f32 v[86:87], v[70:71], v[22:23], v[86:87]
	v_pk_fma_f32 v[80:81], v[40:41], v[24:25], v[80:81]
	v_pk_fma_f32 v[82:83], v[42:43], v[26:27], v[82:83]
	v_pk_fma_f32 v[84:85], v[44:45], v[28:29], v[84:85]
	v_pk_fma_f32 v[86:87], v[46:47], v[30:31], v[86:87]
	v_pk_fma_f32 v[80:81], v[48:49], v[32:33], v[80:81]
	v_pk_fma_f32 v[82:83], v[50:51], v[34:35], v[82:83]
	v_pk_fma_f32 v[84:85], v[52:53], v[36:37], v[84:85]
	v_pk_fma_f32 v[86:87], v[54:55], v[38:39], v[86:87]
	v_cvt_pk_bf16_f32 v88, v80, v81
	v_cvt_pk_bf16_f32 v89, v82, v83
	v_cvt_pk_bf16_f32 v90, v84, v85
	v_cvt_pk_bf16_f32 v91, v86, v87
	global_store_dwordx4 v1, v[88:91], s[10:11] offset:1024
	s_nop 1
	s_waitcnt vmcnt(31)
	v_lshlrev_b32_e32 v56, 16, v184
	v_and_b32_e32 v57, 0xffff0000, v184
	v_lshlrev_b32_e32 v58, 16, v185
	v_and_b32_e32 v59, 0xffff0000, v185
	v_lshlrev_b32_e32 v60, 16, v186
	v_and_b32_e32 v61, 0xffff0000, v186
	v_lshlrev_b32_e32 v62, 16, v187
	v_and_b32_e32 v63, 0xffff0000, v187
	v_pk_fma_f32 v[80:81], v[64:65], v[8:9], v[72:73]
	v_pk_fma_f32 v[82:83], v[66:67], v[10:11], v[74:75]
	v_pk_fma_f32 v[84:85], v[68:69], v[12:13], v[76:77]
	v_pk_fma_f32 v[86:87], v[70:71], v[14:15], v[78:79]
	v_pk_fma_f32 v[80:81], v[40:41], v[16:17], v[80:81]
	v_pk_fma_f32 v[82:83], v[42:43], v[18:19], v[82:83]
	v_pk_fma_f32 v[84:85], v[44:45], v[20:21], v[84:85]
	v_pk_fma_f32 v[86:87], v[46:47], v[22:23], v[86:87]
	v_pk_fma_f32 v[80:81], v[48:49], v[24:25], v[80:81]
	v_pk_fma_f32 v[82:83], v[50:51], v[26:27], v[82:83]
	v_pk_fma_f32 v[84:85], v[52:53], v[28:29], v[84:85]
	v_pk_fma_f32 v[86:87], v[54:55], v[30:31], v[86:87]
	v_pk_fma_f32 v[80:81], v[56:57], v[32:33], v[80:81]
	v_pk_fma_f32 v[82:83], v[58:59], v[34:35], v[82:83]
	v_pk_fma_f32 v[84:85], v[60:61], v[36:37], v[84:85]
	v_pk_fma_f32 v[86:87], v[62:63], v[38:39], v[86:87]
	v_cvt_pk_bf16_f32 v88, v80, v81
	v_cvt_pk_bf16_f32 v89, v82, v83
	v_cvt_pk_bf16_f32 v90, v84, v85
	v_cvt_pk_bf16_f32 v91, v86, v87
	global_store_dwordx4 v1, v[88:91], s[10:11] offset:2048
	s_nop 1
	s_waitcnt vmcnt(31)
	v_lshlrev_b32_e32 v64, 16, v188
	v_and_b32_e32 v65, 0xffff0000, v188
	v_lshlrev_b32_e32 v66, 16, v189
	v_and_b32_e32 v67, 0xffff0000, v189
	v_lshlrev_b32_e32 v68, 16, v190
	v_and_b32_e32 v69, 0xffff0000, v190
	v_lshlrev_b32_e32 v70, 16, v191
	v_and_b32_e32 v71, 0xffff0000, v191
	v_pk_fma_f32 v[80:81], v[40:41], v[8:9], v[72:73]
	v_pk_fma_f32 v[82:83], v[42:43], v[10:11], v[74:75]
	v_pk_fma_f32 v[84:85], v[44:45], v[12:13], v[76:77]
	v_pk_fma_f32 v[86:87], v[46:47], v[14:15], v[78:79]
	v_pk_fma_f32 v[80:81], v[48:49], v[16:17], v[80:81]
	v_pk_fma_f32 v[82:83], v[50:51], v[18:19], v[82:83]
	v_pk_fma_f32 v[84:85], v[52:53], v[20:21], v[84:85]
	v_pk_fma_f32 v[86:87], v[54:55], v[22:23], v[86:87]
	v_pk_fma_f32 v[80:81], v[56:57], v[24:25], v[80:81]
	v_pk_fma_f32 v[82:83], v[58:59], v[26:27], v[82:83]
	v_pk_fma_f32 v[84:85], v[60:61], v[28:29], v[84:85]
	v_pk_fma_f32 v[86:87], v[62:63], v[30:31], v[86:87]
	v_pk_fma_f32 v[80:81], v[64:65], v[32:33], v[80:81]
	v_pk_fma_f32 v[82:83], v[66:67], v[34:35], v[82:83]
	v_pk_fma_f32 v[84:85], v[68:69], v[36:37], v[84:85]
	v_pk_fma_f32 v[86:87], v[70:71], v[38:39], v[86:87]
	v_cvt_pk_bf16_f32 v88, v80, v81
	v_cvt_pk_bf16_f32 v89, v82, v83
	v_cvt_pk_bf16_f32 v90, v84, v85
	v_cvt_pk_bf16_f32 v91, v86, v87
	global_store_dwordx4 v1, v[88:91], s[10:11] offset:3072
	s_nop 1
	s_waitcnt vmcnt(31)
	v_lshlrev_b32_e32 v40, 16, v192
	v_and_b32_e32 v41, 0xffff0000, v192
	v_lshlrev_b32_e32 v42, 16, v193
	v_and_b32_e32 v43, 0xffff0000, v193
	v_lshlrev_b32_e32 v44, 16, v194
	v_and_b32_e32 v45, 0xffff0000, v194
	v_lshlrev_b32_e32 v46, 16, v195
	v_and_b32_e32 v47, 0xffff0000, v195
	v_pk_fma_f32 v[80:81], v[48:49], v[8:9], v[72:73]
	v_pk_fma_f32 v[82:83], v[50:51], v[10:11], v[74:75]
	v_pk_fma_f32 v[84:85], v[52:53], v[12:13], v[76:77]
	v_pk_fma_f32 v[86:87], v[54:55], v[14:15], v[78:79]
	v_pk_fma_f32 v[80:81], v[56:57], v[16:17], v[80:81]
	v_pk_fma_f32 v[82:83], v[58:59], v[18:19], v[82:83]
	v_pk_fma_f32 v[84:85], v[60:61], v[20:21], v[84:85]
	v_pk_fma_f32 v[86:87], v[62:63], v[22:23], v[86:87]
	v_pk_fma_f32 v[80:81], v[64:65], v[24:25], v[80:81]
	v_pk_fma_f32 v[82:83], v[66:67], v[26:27], v[82:83]
	v_pk_fma_f32 v[84:85], v[68:69], v[28:29], v[84:85]
	v_pk_fma_f32 v[86:87], v[70:71], v[30:31], v[86:87]
	v_pk_fma_f32 v[80:81], v[40:41], v[32:33], v[80:81]
	v_pk_fma_f32 v[82:83], v[42:43], v[34:35], v[82:83]
	v_pk_fma_f32 v[84:85], v[44:45], v[36:37], v[84:85]
	v_pk_fma_f32 v[86:87], v[46:47], v[38:39], v[86:87]
	v_cvt_pk_bf16_f32 v88, v80, v81
	v_cvt_pk_bf16_f32 v89, v82, v83
	v_cvt_pk_bf16_f32 v90, v84, v85
	v_cvt_pk_bf16_f32 v91, v86, v87
	s_add_u32 s10, s10, 0x1000
	s_addc_u32 s11, s11, 0
	global_store_dwordx4 v1, v[88:91], s[10:11]
	s_nop 1
	s_waitcnt vmcnt(31)
	v_lshlrev_b32_e32 v48, 16, v196
	v_and_b32_e32 v49, 0xffff0000, v196
	v_lshlrev_b32_e32 v50, 16, v197
	v_and_b32_e32 v51, 0xffff0000, v197
	v_lshlrev_b32_e32 v52, 16, v198
	v_and_b32_e32 v53, 0xffff0000, v198
	v_lshlrev_b32_e32 v54, 16, v199
	v_and_b32_e32 v55, 0xffff0000, v199
	v_pk_fma_f32 v[80:81], v[56:57], v[8:9], v[72:73]
	v_pk_fma_f32 v[82:83], v[58:59], v[10:11], v[74:75]
	v_pk_fma_f32 v[84:85], v[60:61], v[12:13], v[76:77]
	v_pk_fma_f32 v[86:87], v[62:63], v[14:15], v[78:79]
	v_pk_fma_f32 v[80:81], v[64:65], v[16:17], v[80:81]
	v_pk_fma_f32 v[82:83], v[66:67], v[18:19], v[82:83]
	v_pk_fma_f32 v[84:85], v[68:69], v[20:21], v[84:85]
	v_pk_fma_f32 v[86:87], v[70:71], v[22:23], v[86:87]
	v_pk_fma_f32 v[80:81], v[40:41], v[24:25], v[80:81]
	v_pk_fma_f32 v[82:83], v[42:43], v[26:27], v[82:83]
	v_pk_fma_f32 v[84:85], v[44:45], v[28:29], v[84:85]
	v_pk_fma_f32 v[86:87], v[46:47], v[30:31], v[86:87]
	v_pk_fma_f32 v[80:81], v[48:49], v[32:33], v[80:81]
	v_pk_fma_f32 v[82:83], v[50:51], v[34:35], v[82:83]
	v_pk_fma_f32 v[84:85], v[52:53], v[36:37], v[84:85]
	v_pk_fma_f32 v[86:87], v[54:55], v[38:39], v[86:87]
	v_cvt_pk_bf16_f32 v88, v80, v81
	v_cvt_pk_bf16_f32 v89, v82, v83
	v_cvt_pk_bf16_f32 v90, v84, v85
	v_cvt_pk_bf16_f32 v91, v86, v87
	global_store_dwordx4 v1, v[88:91], s[10:11] offset:1024
	s_nop 1
	s_waitcnt vmcnt(31)
	v_lshlrev_b32_e32 v56, 16, v200
	v_and_b32_e32 v57, 0xffff0000, v200
	v_lshlrev_b32_e32 v58, 16, v201
	v_and_b32_e32 v59, 0xffff0000, v201
	v_lshlrev_b32_e32 v60, 16, v202
	v_and_b32_e32 v61, 0xffff0000, v202
	v_lshlrev_b32_e32 v62, 16, v203
	v_and_b32_e32 v63, 0xffff0000, v203
	v_pk_fma_f32 v[80:81], v[64:65], v[8:9], v[72:73]
	v_pk_fma_f32 v[82:83], v[66:67], v[10:11], v[74:75]
	v_pk_fma_f32 v[84:85], v[68:69], v[12:13], v[76:77]
	v_pk_fma_f32 v[86:87], v[70:71], v[14:15], v[78:79]
	v_pk_fma_f32 v[80:81], v[40:41], v[16:17], v[80:81]
	v_pk_fma_f32 v[82:83], v[42:43], v[18:19], v[82:83]
	v_pk_fma_f32 v[84:85], v[44:45], v[20:21], v[84:85]
	v_pk_fma_f32 v[86:87], v[46:47], v[22:23], v[86:87]
	v_pk_fma_f32 v[80:81], v[48:49], v[24:25], v[80:81]
	v_pk_fma_f32 v[82:83], v[50:51], v[26:27], v[82:83]
	v_pk_fma_f32 v[84:85], v[52:53], v[28:29], v[84:85]
	v_pk_fma_f32 v[86:87], v[54:55], v[30:31], v[86:87]
	v_pk_fma_f32 v[80:81], v[56:57], v[32:33], v[80:81]
	v_pk_fma_f32 v[82:83], v[58:59], v[34:35], v[82:83]
	v_pk_fma_f32 v[84:85], v[60:61], v[36:37], v[84:85]
	v_pk_fma_f32 v[86:87], v[62:63], v[38:39], v[86:87]
	v_cvt_pk_bf16_f32 v88, v80, v81
	v_cvt_pk_bf16_f32 v89, v82, v83
	v_cvt_pk_bf16_f32 v90, v84, v85
	v_cvt_pk_bf16_f32 v91, v86, v87
	global_store_dwordx4 v1, v[88:91], s[10:11] offset:2048
	s_nop 1
	s_waitcnt vmcnt(31)
	v_lshlrev_b32_e32 v64, 16, v204
	v_and_b32_e32 v65, 0xffff0000, v204
	v_lshlrev_b32_e32 v66, 16, v205
	v_and_b32_e32 v67, 0xffff0000, v205
	v_lshlrev_b32_e32 v68, 16, v206
	v_and_b32_e32 v69, 0xffff0000, v206
	v_lshlrev_b32_e32 v70, 16, v207
	v_and_b32_e32 v71, 0xffff0000, v207
	v_pk_fma_f32 v[80:81], v[40:41], v[8:9], v[72:73]
	v_pk_fma_f32 v[82:83], v[42:43], v[10:11], v[74:75]
	v_pk_fma_f32 v[84:85], v[44:45], v[12:13], v[76:77]
	v_pk_fma_f32 v[86:87], v[46:47], v[14:15], v[78:79]
	v_pk_fma_f32 v[80:81], v[48:49], v[16:17], v[80:81]
	v_pk_fma_f32 v[82:83], v[50:51], v[18:19], v[82:83]
	v_pk_fma_f32 v[84:85], v[52:53], v[20:21], v[84:85]
	v_pk_fma_f32 v[86:87], v[54:55], v[22:23], v[86:87]
	v_pk_fma_f32 v[80:81], v[56:57], v[24:25], v[80:81]
	v_pk_fma_f32 v[82:83], v[58:59], v[26:27], v[82:83]
	v_pk_fma_f32 v[84:85], v[60:61], v[28:29], v[84:85]
	v_pk_fma_f32 v[86:87], v[62:63], v[30:31], v[86:87]
	v_pk_fma_f32 v[80:81], v[64:65], v[32:33], v[80:81]
	v_pk_fma_f32 v[82:83], v[66:67], v[34:35], v[82:83]
	v_pk_fma_f32 v[84:85], v[68:69], v[36:37], v[84:85]
	v_pk_fma_f32 v[86:87], v[70:71], v[38:39], v[86:87]
	v_cvt_pk_bf16_f32 v88, v80, v81
	v_cvt_pk_bf16_f32 v89, v82, v83
	v_cvt_pk_bf16_f32 v90, v84, v85
	v_cvt_pk_bf16_f32 v91, v86, v87
	global_store_dwordx4 v1, v[88:91], s[10:11] offset:3072
	s_nop 1
	s_waitcnt vmcnt(31)
	v_lshlrev_b32_e32 v40, 16, v208
	v_and_b32_e32 v41, 0xffff0000, v208
	v_lshlrev_b32_e32 v42, 16, v209
	v_and_b32_e32 v43, 0xffff0000, v209
	v_lshlrev_b32_e32 v44, 16, v210
	v_and_b32_e32 v45, 0xffff0000, v210
	v_lshlrev_b32_e32 v46, 16, v211
	v_and_b32_e32 v47, 0xffff0000, v211
	v_pk_fma_f32 v[80:81], v[48:49], v[8:9], v[72:73]
	v_pk_fma_f32 v[82:83], v[50:51], v[10:11], v[74:75]
	v_pk_fma_f32 v[84:85], v[52:53], v[12:13], v[76:77]
	v_pk_fma_f32 v[86:87], v[54:55], v[14:15], v[78:79]
	v_pk_fma_f32 v[80:81], v[56:57], v[16:17], v[80:81]
	v_pk_fma_f32 v[82:83], v[58:59], v[18:19], v[82:83]
	v_pk_fma_f32 v[84:85], v[60:61], v[20:21], v[84:85]
	v_pk_fma_f32 v[86:87], v[62:63], v[22:23], v[86:87]
	v_pk_fma_f32 v[80:81], v[64:65], v[24:25], v[80:81]
	v_pk_fma_f32 v[82:83], v[66:67], v[26:27], v[82:83]
	v_pk_fma_f32 v[84:85], v[68:69], v[28:29], v[84:85]
	v_pk_fma_f32 v[86:87], v[70:71], v[30:31], v[86:87]
	v_pk_fma_f32 v[80:81], v[40:41], v[32:33], v[80:81]
	v_pk_fma_f32 v[82:83], v[42:43], v[34:35], v[82:83]
	v_pk_fma_f32 v[84:85], v[44:45], v[36:37], v[84:85]
	v_pk_fma_f32 v[86:87], v[46:47], v[38:39], v[86:87]
	v_cvt_pk_bf16_f32 v88, v80, v81
	v_cvt_pk_bf16_f32 v89, v82, v83
	v_cvt_pk_bf16_f32 v90, v84, v85
	v_cvt_pk_bf16_f32 v91, v86, v87
	s_add_u32 s10, s10, 0x1000
	s_addc_u32 s11, s11, 0
	global_store_dwordx4 v1, v[88:91], s[10:11]
	s_nop 1
	s_waitcnt vmcnt(31)
	v_lshlrev_b32_e32 v48, 16, v212
	v_and_b32_e32 v49, 0xffff0000, v212
	v_lshlrev_b32_e32 v50, 16, v213
	v_and_b32_e32 v51, 0xffff0000, v213
	v_lshlrev_b32_e32 v52, 16, v214
	v_and_b32_e32 v53, 0xffff0000, v214
	v_lshlrev_b32_e32 v54, 16, v215
	v_and_b32_e32 v55, 0xffff0000, v215
	v_pk_fma_f32 v[80:81], v[56:57], v[8:9], v[72:73]
	v_pk_fma_f32 v[82:83], v[58:59], v[10:11], v[74:75]
	v_pk_fma_f32 v[84:85], v[60:61], v[12:13], v[76:77]
	v_pk_fma_f32 v[86:87], v[62:63], v[14:15], v[78:79]
	v_pk_fma_f32 v[80:81], v[64:65], v[16:17], v[80:81]
	v_pk_fma_f32 v[82:83], v[66:67], v[18:19], v[82:83]
	v_pk_fma_f32 v[84:85], v[68:69], v[20:21], v[84:85]
	v_pk_fma_f32 v[86:87], v[70:71], v[22:23], v[86:87]
	v_pk_fma_f32 v[80:81], v[40:41], v[24:25], v[80:81]
	v_pk_fma_f32 v[82:83], v[42:43], v[26:27], v[82:83]
	v_pk_fma_f32 v[84:85], v[44:45], v[28:29], v[84:85]
	v_pk_fma_f32 v[86:87], v[46:47], v[30:31], v[86:87]
	v_pk_fma_f32 v[80:81], v[48:49], v[32:33], v[80:81]
	v_pk_fma_f32 v[82:83], v[50:51], v[34:35], v[82:83]
	v_pk_fma_f32 v[84:85], v[52:53], v[36:37], v[84:85]
	v_pk_fma_f32 v[86:87], v[54:55], v[38:39], v[86:87]
	v_cvt_pk_bf16_f32 v88, v80, v81
	v_cvt_pk_bf16_f32 v89, v82, v83
	v_cvt_pk_bf16_f32 v90, v84, v85
	v_cvt_pk_bf16_f32 v91, v86, v87
	global_store_dwordx4 v1, v[88:91], s[10:11] offset:1024
	s_nop 1
	s_waitcnt vmcnt(31)
	v_lshlrev_b32_e32 v56, 16, v216
	v_and_b32_e32 v57, 0xffff0000, v216
	v_lshlrev_b32_e32 v58, 16, v217
	v_and_b32_e32 v59, 0xffff0000, v217
	v_lshlrev_b32_e32 v60, 16, v218
	v_and_b32_e32 v61, 0xffff0000, v218
	v_lshlrev_b32_e32 v62, 16, v219
	v_and_b32_e32 v63, 0xffff0000, v219
	v_pk_fma_f32 v[80:81], v[64:65], v[8:9], v[72:73]
	v_pk_fma_f32 v[82:83], v[66:67], v[10:11], v[74:75]
	v_pk_fma_f32 v[84:85], v[68:69], v[12:13], v[76:77]
	v_pk_fma_f32 v[86:87], v[70:71], v[14:15], v[78:79]
	v_pk_fma_f32 v[80:81], v[40:41], v[16:17], v[80:81]
	v_pk_fma_f32 v[82:83], v[42:43], v[18:19], v[82:83]
	v_pk_fma_f32 v[84:85], v[44:45], v[20:21], v[84:85]
	v_pk_fma_f32 v[86:87], v[46:47], v[22:23], v[86:87]
	v_pk_fma_f32 v[80:81], v[48:49], v[24:25], v[80:81]
	v_pk_fma_f32 v[82:83], v[50:51], v[26:27], v[82:83]
	v_pk_fma_f32 v[84:85], v[52:53], v[28:29], v[84:85]
	v_pk_fma_f32 v[86:87], v[54:55], v[30:31], v[86:87]
	v_pk_fma_f32 v[80:81], v[56:57], v[32:33], v[80:81]
	v_pk_fma_f32 v[82:83], v[58:59], v[34:35], v[82:83]
	v_pk_fma_f32 v[84:85], v[60:61], v[36:37], v[84:85]
	v_pk_fma_f32 v[86:87], v[62:63], v[38:39], v[86:87]
	v_cvt_pk_bf16_f32 v88, v80, v81
	v_cvt_pk_bf16_f32 v89, v82, v83
	v_cvt_pk_bf16_f32 v90, v84, v85
	v_cvt_pk_bf16_f32 v91, v86, v87
	global_store_dwordx4 v1, v[88:91], s[10:11] offset:2048
	s_nop 1
	s_waitcnt vmcnt(31)
	v_lshlrev_b32_e32 v64, 16, v220
	v_and_b32_e32 v65, 0xffff0000, v220
	v_lshlrev_b32_e32 v66, 16, v221
	v_and_b32_e32 v67, 0xffff0000, v221
	v_lshlrev_b32_e32 v68, 16, v222
	v_and_b32_e32 v69, 0xffff0000, v222
	v_lshlrev_b32_e32 v70, 16, v223
	v_and_b32_e32 v71, 0xffff0000, v223
	v_pk_fma_f32 v[80:81], v[40:41], v[8:9], v[72:73]
	v_pk_fma_f32 v[82:83], v[42:43], v[10:11], v[74:75]
	v_pk_fma_f32 v[84:85], v[44:45], v[12:13], v[76:77]
	v_pk_fma_f32 v[86:87], v[46:47], v[14:15], v[78:79]
	v_pk_fma_f32 v[80:81], v[48:49], v[16:17], v[80:81]
	v_pk_fma_f32 v[82:83], v[50:51], v[18:19], v[82:83]
	v_pk_fma_f32 v[84:85], v[52:53], v[20:21], v[84:85]
	v_pk_fma_f32 v[86:87], v[54:55], v[22:23], v[86:87]
	v_pk_fma_f32 v[80:81], v[56:57], v[24:25], v[80:81]
	v_pk_fma_f32 v[82:83], v[58:59], v[26:27], v[82:83]
	v_pk_fma_f32 v[84:85], v[60:61], v[28:29], v[84:85]
	v_pk_fma_f32 v[86:87], v[62:63], v[30:31], v[86:87]
	v_pk_fma_f32 v[80:81], v[64:65], v[32:33], v[80:81]
	v_pk_fma_f32 v[82:83], v[66:67], v[34:35], v[82:83]
	v_pk_fma_f32 v[84:85], v[68:69], v[36:37], v[84:85]
	v_pk_fma_f32 v[86:87], v[70:71], v[38:39], v[86:87]
	v_cvt_pk_bf16_f32 v88, v80, v81
	v_cvt_pk_bf16_f32 v89, v82, v83
	v_cvt_pk_bf16_f32 v90, v84, v85
	v_cvt_pk_bf16_f32 v91, v86, v87
	global_store_dwordx4 v1, v[88:91], s[10:11] offset:3072
	s_nop 1
	s_waitcnt vmcnt(31)
	v_lshlrev_b32_e32 v40, 16, v224
	v_and_b32_e32 v41, 0xffff0000, v224
	v_lshlrev_b32_e32 v42, 16, v225
	v_and_b32_e32 v43, 0xffff0000, v225
	v_lshlrev_b32_e32 v44, 16, v226
	v_and_b32_e32 v45, 0xffff0000, v226
	v_lshlrev_b32_e32 v46, 16, v227
	v_and_b32_e32 v47, 0xffff0000, v227
	v_pk_fma_f32 v[80:81], v[48:49], v[8:9], v[72:73]
	v_pk_fma_f32 v[82:83], v[50:51], v[10:11], v[74:75]
	v_pk_fma_f32 v[84:85], v[52:53], v[12:13], v[76:77]
	v_pk_fma_f32 v[86:87], v[54:55], v[14:15], v[78:79]
	v_pk_fma_f32 v[80:81], v[56:57], v[16:17], v[80:81]
	v_pk_fma_f32 v[82:83], v[58:59], v[18:19], v[82:83]
	v_pk_fma_f32 v[84:85], v[60:61], v[20:21], v[84:85]
	v_pk_fma_f32 v[86:87], v[62:63], v[22:23], v[86:87]
	v_pk_fma_f32 v[80:81], v[64:65], v[24:25], v[80:81]
	v_pk_fma_f32 v[82:83], v[66:67], v[26:27], v[82:83]
	v_pk_fma_f32 v[84:85], v[68:69], v[28:29], v[84:85]
	v_pk_fma_f32 v[86:87], v[70:71], v[30:31], v[86:87]
	v_pk_fma_f32 v[80:81], v[40:41], v[32:33], v[80:81]
	v_pk_fma_f32 v[82:83], v[42:43], v[34:35], v[82:83]
	v_pk_fma_f32 v[84:85], v[44:45], v[36:37], v[84:85]
	v_pk_fma_f32 v[86:87], v[46:47], v[38:39], v[86:87]
	v_cvt_pk_bf16_f32 v88, v80, v81
	v_cvt_pk_bf16_f32 v89, v82, v83
	v_cvt_pk_bf16_f32 v90, v84, v85
	v_cvt_pk_bf16_f32 v91, v86, v87
	s_add_u32 s10, s10, 0x1000
	s_addc_u32 s11, s11, 0
	global_store_dwordx4 v1, v[88:91], s[10:11]
	s_nop 1
	s_waitcnt vmcnt(31)
	v_lshlrev_b32_e32 v48, 16, v228
	v_and_b32_e32 v49, 0xffff0000, v228
	v_lshlrev_b32_e32 v50, 16, v229
	v_and_b32_e32 v51, 0xffff0000, v229
	v_lshlrev_b32_e32 v52, 16, v230
	v_and_b32_e32 v53, 0xffff0000, v230
	v_lshlrev_b32_e32 v54, 16, v231
	v_and_b32_e32 v55, 0xffff0000, v231
	v_pk_fma_f32 v[80:81], v[56:57], v[8:9], v[72:73]
	v_pk_fma_f32 v[82:83], v[58:59], v[10:11], v[74:75]
	v_pk_fma_f32 v[84:85], v[60:61], v[12:13], v[76:77]
	v_pk_fma_f32 v[86:87], v[62:63], v[14:15], v[78:79]
	v_pk_fma_f32 v[80:81], v[64:65], v[16:17], v[80:81]
	v_pk_fma_f32 v[82:83], v[66:67], v[18:19], v[82:83]
	v_pk_fma_f32 v[84:85], v[68:69], v[20:21], v[84:85]
	v_pk_fma_f32 v[86:87], v[70:71], v[22:23], v[86:87]
	v_pk_fma_f32 v[80:81], v[40:41], v[24:25], v[80:81]
	v_pk_fma_f32 v[82:83], v[42:43], v[26:27], v[82:83]
	v_pk_fma_f32 v[84:85], v[44:45], v[28:29], v[84:85]
	v_pk_fma_f32 v[86:87], v[46:47], v[30:31], v[86:87]
	v_pk_fma_f32 v[80:81], v[48:49], v[32:33], v[80:81]
	v_pk_fma_f32 v[82:83], v[50:51], v[34:35], v[82:83]
	v_pk_fma_f32 v[84:85], v[52:53], v[36:37], v[84:85]
	v_pk_fma_f32 v[86:87], v[54:55], v[38:39], v[86:87]
	v_cvt_pk_bf16_f32 v88, v80, v81
	v_cvt_pk_bf16_f32 v89, v82, v83
	v_cvt_pk_bf16_f32 v90, v84, v85
	v_cvt_pk_bf16_f32 v91, v86, v87
	global_store_dwordx4 v1, v[88:91], s[10:11] offset:1024
	s_nop 1
	s_waitcnt vmcnt(31)
	v_lshlrev_b32_e32 v56, 16, v232
	v_and_b32_e32 v57, 0xffff0000, v232
	v_lshlrev_b32_e32 v58, 16, v233
	v_and_b32_e32 v59, 0xffff0000, v233
	v_lshlrev_b32_e32 v60, 16, v234
	v_and_b32_e32 v61, 0xffff0000, v234
	v_lshlrev_b32_e32 v62, 16, v235
	v_and_b32_e32 v63, 0xffff0000, v235
	v_pk_fma_f32 v[80:81], v[64:65], v[8:9], v[72:73]
	v_pk_fma_f32 v[82:83], v[66:67], v[10:11], v[74:75]
	v_pk_fma_f32 v[84:85], v[68:69], v[12:13], v[76:77]
	v_pk_fma_f32 v[86:87], v[70:71], v[14:15], v[78:79]
	v_pk_fma_f32 v[80:81], v[40:41], v[16:17], v[80:81]
	v_pk_fma_f32 v[82:83], v[42:43], v[18:19], v[82:83]
	v_pk_fma_f32 v[84:85], v[44:45], v[20:21], v[84:85]
	v_pk_fma_f32 v[86:87], v[46:47], v[22:23], v[86:87]
	v_pk_fma_f32 v[80:81], v[48:49], v[24:25], v[80:81]
	v_pk_fma_f32 v[82:83], v[50:51], v[26:27], v[82:83]
	v_pk_fma_f32 v[84:85], v[52:53], v[28:29], v[84:85]
	v_pk_fma_f32 v[86:87], v[54:55], v[30:31], v[86:87]
	v_pk_fma_f32 v[80:81], v[56:57], v[32:33], v[80:81]
	v_pk_fma_f32 v[82:83], v[58:59], v[34:35], v[82:83]
	v_pk_fma_f32 v[84:85], v[60:61], v[36:37], v[84:85]
	v_pk_fma_f32 v[86:87], v[62:63], v[38:39], v[86:87]
	v_cvt_pk_bf16_f32 v88, v80, v81
	v_cvt_pk_bf16_f32 v89, v82, v83
	v_cvt_pk_bf16_f32 v90, v84, v85
	v_cvt_pk_bf16_f32 v91, v86, v87
	global_store_dwordx4 v1, v[88:91], s[10:11] offset:2048
	s_nop 1
	s_waitcnt vmcnt(31)
	v_lshlrev_b32_e32 v64, 16, v236
	v_and_b32_e32 v65, 0xffff0000, v236
	v_lshlrev_b32_e32 v66, 16, v237
	v_and_b32_e32 v67, 0xffff0000, v237
	v_lshlrev_b32_e32 v68, 16, v238
	v_and_b32_e32 v69, 0xffff0000, v238
	v_lshlrev_b32_e32 v70, 16, v239
	v_and_b32_e32 v71, 0xffff0000, v239
	v_pk_fma_f32 v[80:81], v[40:41], v[8:9], v[72:73]
	v_pk_fma_f32 v[82:83], v[42:43], v[10:11], v[74:75]
	v_pk_fma_f32 v[84:85], v[44:45], v[12:13], v[76:77]
	v_pk_fma_f32 v[86:87], v[46:47], v[14:15], v[78:79]
	v_pk_fma_f32 v[80:81], v[48:49], v[16:17], v[80:81]
	v_pk_fma_f32 v[82:83], v[50:51], v[18:19], v[82:83]
	v_pk_fma_f32 v[84:85], v[52:53], v[20:21], v[84:85]
	v_pk_fma_f32 v[86:87], v[54:55], v[22:23], v[86:87]
	v_pk_fma_f32 v[80:81], v[56:57], v[24:25], v[80:81]
	v_pk_fma_f32 v[82:83], v[58:59], v[26:27], v[82:83]
	v_pk_fma_f32 v[84:85], v[60:61], v[28:29], v[84:85]
	v_pk_fma_f32 v[86:87], v[62:63], v[30:31], v[86:87]
	v_pk_fma_f32 v[80:81], v[64:65], v[32:33], v[80:81]
	v_pk_fma_f32 v[82:83], v[66:67], v[34:35], v[82:83]
	v_pk_fma_f32 v[84:85], v[68:69], v[36:37], v[84:85]
	v_pk_fma_f32 v[86:87], v[70:71], v[38:39], v[86:87]
	v_cvt_pk_bf16_f32 v88, v80, v81
	v_cvt_pk_bf16_f32 v89, v82, v83
	v_cvt_pk_bf16_f32 v90, v84, v85
	v_cvt_pk_bf16_f32 v91, v86, v87
	global_store_dwordx4 v1, v[88:91], s[10:11] offset:3072
	s_nop 1
	s_branch .Lp2b_done
.Lp2b_compiled:
	s_mov_b64 s[34:35], 0x400000
	v_cmp_gt_u64_e32 vcc, s[34:35], v[44:45]
	s_and_saveexec_b64 s[38:39], vcc
	s_cbranch_execz .LBB0_678
	v_and_b32_e32 v42, 0x1f8, v56
	v_mov_b32_e32 v90, 0
	v_lshlrev_b32_e32 v20, 2, v42
	v_mov_b32_e32 v21, v90
	v_lshl_add_u64 v[32:33], s[70:71], 0, v[20:21]
	global_load_dwordx4 v[0:3], v20, s[72:73]
	global_load_dwordx4 v[4:7], v20, s[70:71]
	global_load_dwordx4 v[8:11], v20, s[72:73] offset:16
	global_load_dwordx4 v[12:15], v20, s[70:71] offset:16
	global_load_dwordx4 v[16:19], v20, s[70:71] offset:2048
	s_nop 0
	global_load_dwordx4 v[20:23], v20, s[70:71] offset:2064
	s_mov_b64 s[0:1], 0x1000
	v_lshl_add_u64 v[28:29], v[32:33], 0, s[0:1]
	s_movk_i32 s0, 0x1000
	v_add_co_u32_e32 v34, vcc, s0, v32
	s_mov_b64 s[0:1], 0x1800
	s_nop 0
	v_addc_co_u32_e32 v35, vcc, 0, v33, vcc
	v_lshl_add_u64 v[36:37], v[32:33], 0, s[0:1]
	global_load_dwordx4 v[24:27], v[34:35], off
	s_nop 0
	global_load_dwordx4 v[28:31], v[28:29], off offset:16
	s_nop 0
	global_load_dwordx4 v[32:35], v[34:35], off offset:2048
	s_nop 0
	global_load_dwordx4 v[36:39], v[36:37], off offset:16
	v_lshlrev_b32_e32 v42, 1, v42
	v_mov_b32_e32 v43, v90
	v_lshl_add_u64 v[42:43], s[96:97], 0, v[42:43]
	s_mov_b64 s[0:1], 0x1d800000
	v_lshl_add_u64 v[92:93], v[42:43], 0, s[0:1]
	s_mov_b64 s[0:1], 0x27800000
	v_lshl_add_u64 v[94:95], v[42:43], 0, s[0:1]
	s_lshl_b64 s[40:41], s[20:21], 14
	s_lshl_b64 s[42:43], s[20:21], 10
	s_lshl_b64 s[50:51], s[20:21], 13
	s_lshl_b64 s[0:1], s[2:3], 12
	s_lshl_b64 s[4:5], s[22:23], 3
	s_add_u32 s0, s4, s0
	s_addc_u32 s1, s5, s1
	v_lshl_add_u64 v[96:97], v[40:41], 3, s[0:1]
	s_lshl_b64 s[54:55], s[20:21], 12
	s_mov_b64 s[56:57], 0
	s_mov_b64 s[68:69], 0x3fffff
	s_branch .LBB0_672

.LBB0_679:
.Lp2b_done:
	s_cmp_gt_i32 s89, 3
	s_cselect_b64 s[0:1], -1, 0
	s_and_b64 s[4:5], s[26:27], s[0:1]
	s_andn2_b64 vcc, exec, s[4:5]
	s_cbranch_vccnz .LBB0_733
	s_waitcnt vmcnt(0)
	s_waitcnt vmcnt(0)
	s_barrier
	s_mov_b64 s[4:5], exec
	v_readlane_b32 s6, v255, 5
	v_readlane_b32 s7, v255, 6
	s_and_b64 s[6:7], s[4:5], s[6:7]
	s_mov_b64 exec, s[6:7]
	s_cbranch_execz .LBB0_732
	s_add_i32 s3, 0, 0x20140
	v_mov_b32_e32 v0, s3
	s_waitcnt vmcnt(0) expcnt(0) lgkmcnt(0)
	ds_read_b32 v2, v0
	s_add_i32 s3, 0, 0x20144
	v_mov_b32_e32 v0, s3
	ds_read_b32 v0, v0
	s_waitcnt lgkmcnt(1)
	v_cmp_ne_u32_e32 vcc, 0, v2
	s_cbranch_vccnz .LBB0_696
	s_add_u32 s6, s96, 0x2e00200
	s_addc_u32 s7, s97, 0
	s_add_u32 s8, s96, 0x2e00400
	s_addc_u32 s9, s97, 0
	s_add_u32 s10, s96, 0x2e00500
	s_addc_u32 s11, s97, 0
	s_add_u32 s12, s96, 0x2e00600
	s_addc_u32 s13, s97, 0
	s_add_u32 s14, s96, 0x2e00700
	s_addc_u32 s15, s97, 0
	s_add_u32 s16, s96, 0x2e00800
	s_addc_u32 s17, s97, 0
	s_add_u32 s18, s96, 0x2e00900
	s_addc_u32 s19, s97, 0
	s_add_u32 s20, s96, 0x2e00a00
	s_addc_u32 s21, s97, 0
	s_add_u32 s22, s96, 0x2e00b00
	s_addc_u32 s23, s97, 0
	s_add_u32 s26, s96, 0x2e00c00
	s_addc_u32 s27, s97, 0
	s_add_u32 s28, s96, 0x2e00d00
	s_addc_u32 s29, s97, 0
	s_add_u32 s30, s96, 0x2e00e00
	s_addc_u32 s31, s97, 0
	s_add_u32 s34, s96, 0x2e00f00
	s_addc_u32 s35, s97, 0
	s_add_u32 s38, s96, 0x2e01000
	s_addc_u32 s39, s97, 0
	s_add_u32 s40, s96, 0x2e01100
	s_addc_u32 s41, s97, 0
	s_add_u32 s42, s96, 0x2e01200
	v_readlane_b32 s3, v255, 4
	s_addc_u32 s43, s97, 0
	s_mul_i32 s3, s93, s3
	s_add_u32 s50, s96, 0x2e01300
	s_mul_i32 s3, s3, s92
	s_addc_u32 s51, s97, 0
	s_mov_b32 s52, 1
	v_mov_b32_e32 v16, 0
	s_branch .LBB0_684
